# attention prefetch now covers the RoPE table rows; first item's rows (incl. rope) touched at the start of the state item
# baseline (speedup 1.0000x reference)
; __device__ __forceinline__ void mlstm_state_group(const Args& a, LAS unsigned char* lds, int bh, int grp, int tid, int wave, int lane) {
;     const int b = bh >> 2, h = bh & 3;
;     const bf16_t* P = (const bf16_t*)(a.ws + WS_ACT);
;     const float* GT = (const float*)(a.ws + WS_GATES);
;     float* CG = (float*)(a.ws + WS_CG); float* NGs = (float*)(a.ws + WS_NG); float* SG = (float*)(a.ws + WS_SG); float* CHS = (float*)(a.ws + WS_CHS);
;     LAS bf16_t* VT = (LAS bf16_t*)(lds + ML2_VT); LAS bf16_t* KWT = (LAS bf16_t*)(lds + ML2_KWT);
;     LAS float* T_av = (LAS float*)(lds + ML_TB); LAS float* T_sc = T_av + 2048;
; __device__ __forceinline__ void attn_item(const Args& a, LAS unsigned char* lds, int item, int tid, int wave, int lane) {
;     const int qb = item & 31, kvh = (item >> 5) & 1, b = item >> 6;
;     const int q0 = qb * 64;
;     const bf16_t* P = (const bf16_t*)(a.ws + WS_ACT);
;     const float* rope = (const float*)(a.ws + WS_ROPE);
;     bf16_t* HO = (bf16_t*)(a.ws + WS_HO);
;     LAS bf16_t* KS = (LAS bf16_t*)(lds + AT_KS); LAS bf16_t* VT = (LAS bf16_t*)(lds + AT_VT); LAS bf16_t* QS = (LAS bf16_t*)(lds + AT_QS);
;     LAS bf16_t* PS = (LAS bf16_t*)(lds + AT_PS) + wave * 16 * VP;
;     const int fr = lane & 15, fq = lane >> 4;
;     const size_t rowbase = (size_t)b * SEQ;
;     const int grp = tid & 3;
;     u32x4 kk[2][2], vv[2][2], qq[2][2]; f32x4 tk[2][4], tq[2][4];
; #pragma unroll
;     for (int it = 0; it < 2; ++it) {
;         const int t = tid + 512 * it;
;         const int kc = (t >> 2) < 192 ? (t >> 2) : 191, kpos = q0 - 128 + kc, kposc = kpos < 0 ? 0 : kpos;
;         const bf16_t* kp = P + (rowbase + kposc) * NIN + PC_KA + kvh * 64 + grp * 16; kk[it][0] = *(const u32x4*)kp; kk[it][1] = *(const u32x4*)(kp + 8);
;         const bf16_t* vp = P + (rowbase + kposc) * NIN + PC_VA + kvh * 64 + grp * 16; vv[it][0] = *(const u32x4*)vp; vv[it][1] = *(const u32x4*)(vp + 8);
;         const float* tkp = rope + (rowbase + kposc) * 16;
; #pragma unroll
;         for (int q = 0; q < 4; ++q) tk[it][q] = *(const f32x4*)(tkp + 4 * q);
;         const int qi = (t >> 2) & 63, gq = t >> 8;
;         const size_t row = rowbase + q0 + qi;
;         const bf16_t* qp = P + row * NIN + PC_QA + (kvh * 4 + gq) * 64 + grp * 16; qq[it][0] = *(const u32x4*)qp; qq[it][1] = *(const u32x4*)(qp + 8);
;         const float* tqp = rope + row * 16;
.LBB0_1078:
.LBB0_1079:
	s_mov_b32 s32, s81
	s_bfe_u32 s53, s32, 0x10005
	s_lshr_b32 s54, s32, 6
	s_lshl_b32 s55, s92, 1
	s_add_i32 s54, s54, s55
	s_lshl_b32 s54, s54, 11
	s_lshl_b32 s55, s81, 6
	s_add_i32 s70, s54, s55
	s_add_i32 s71, s55, 0xffffff80
	s_lshl_b32 s79, s53, 7
	s_add_i32 s79, s79, 0x1000
	s_lshl_b32 s80, s53, 9
	s_add_i32 s80, s80, 0xc00
	s_movk_i32 s82, 0x2400
	s_movk_i32 s83, 0xc0
	v_add_u32_e32 v148, s71, v153
	v_max_i32_e32 v148, 0, v148
	v_add_u32_e32 v148, s54, v148
	v_mul_lo_u32 v148, v148, s82
	v_add_u32_e32 v148, s79, v148
	v_subrev_u32_e32 v149, s83, v153
	v_min_u32_e32 v149, 0xff, v149
	v_lshrrev_b32_e32 v150, 2, v149
	v_and_b32_e32 v149, 3, v149
	v_add_u32_e32 v150, s70, v150
	v_mul_lo_u32 v150, v150, s82
	v_lshl_add_u32 v150, v149, 7, v150
	v_add_u32_e32 v150, s80, v150
	v_cmp_gt_u32_e64 s[66:67], s83, v153
	s_nop 1
	v_cndmask_b32_e64 v148, v150, v148, s[66:67]
	global_load_dword v151, v148, s[68:69]
	global_load_dword v151, v148, s[68:69] offset:256
	s_add_u32 s84, s74, 0x3100000
	s_addc_u32 s85, s75, 0
	v_min_u32_e32 v244, 0xbf, v153
	v_add_u32_e32 v244, s71, v244
	v_max_i32_e32 v244, 0, v244
	v_add_lshl_u32 v244, s54, v244, 6
	global_load_dword v151, v244, s[84:85]
	s_mul_hi_i32 s0, s81, 0x2aaaaaab
	s_lshr_b32 s1, s0, 31
	s_ashr_i32 s0, s0, 1
	s_add_i32 s0, s0, s1
	s_mul_i32 s1, s0, 12
	s_sub_i32 s1, s81, s1
	s_lshl_b32 s4, s92, 3
	s_lshl_b32 s0, s0, 2
	s_add_i32 s0, s0, s4
	s_mul_i32 s4, s1, 0x56
	s_bfe_u32 s5, s4, 0x1000f
	s_bfe_u32 s4, s4, 0x80008
	s_add_i32 s4, s4, s5
	s_sext_i32_i8 s5, s4
	s_mul_i32 s4, s4, 3
	s_add_i32 s0, s0, s5
	s_sub_i32 s1, s1, s4
	s_sext_i32_i8 s1, s1
	s_ashr_i32 s6, s0, 2
	s_lshl_b32 s10, s1, 3
	s_ashr_i32 s7, s6, 31
	s_lshl_b64 s[12:13], s[6:7], 11
	v_and_b32_e32 v109, 31, v153
	s_ashr_i32 s11, s10, 31
	v_lshl_or_b32 v4, v109, 1, s12
	v_mov_b32_e32 v5, s13
	s_lshl_b64 s[8:9], s[10:11], 6
	v_lshl_add_u64 v[6:7], v[4:5], 0, s[8:9]
	s_movk_i32 s25, 0x2400
	v_mov_b64_e32 v[2:3], s[68:69]
	s_and_b32 s14, s5, 3
	s_mov_b32 s5, 0
	v_mad_u64_u32 v[8:9], s[8:9], v6, s25, v[2:3]
	s_lshl_b32 s4, s14, 2
	v_lshrrev_b32_e32 v108, 5, v153
	v_mov_b32_e32 v1, 0
	v_mad_i32_i24 v9, v7, s25, v9
	s_lshl_b32 s8, s14, 8
	s_mov_b32 s9, s5
	v_mov_b32_e32 v0, s4
	s_lshl_b32 s6, s14, 7
	s_mov_b32 s7, s5
	s_waitcnt lgkmcnt(0)
	v_lshl_add_u64 v[10:11], v[8:9], 0, s[8:9]
	v_lshlrev_b32_e32 v6, 4, v108
	v_mov_b32_e32 v7, v1
	global_load_dword v28, v0, s[56:57]
	global_load_dword v16, v0, s[58:59]
	v_lshlrev_b32_e32 v0, 3, v108
	v_lshl_add_u64 v[10:11], v[10:11], 0, v[6:7]
	v_lshl_add_u64 v[8:9], v[8:9], 0, s[6:7]
	s_movk_i32 s24, 0x2000
	v_lshl_add_u64 v[8:9], v[8:9], 0, v[0:1]
	global_load_dwordx4 v[48:51], v[10:11], off offset:1024
	global_load_dwordx2 v[94:95], v[8:9], off offset:512
	v_add_co_u32_e32 v10, vcc, s24, v10
	s_or_b32 s14, s10, 1
	s_nop 0
	v_addc_co_u32_e32 v11, vcc, 0, v11, vcc
	v_add_co_u32_e32 v8, vcc, s24, v8
	s_ashr_i32 s15, s14, 31
	s_nop 0
	v_addc_co_u32_e32 v9, vcc, 0, v9, vcc
	s_lshl_b64 s[14:15], s[14:15], 6
	global_load_dwordx4 v[52:55], v[10:11], off offset:2048
	global_load_dwordx2 v[96:97], v[8:9], off offset:1536
	v_lshl_add_u64 v[8:9], v[4:5], 0, s[14:15]
	v_mad_u64_u32 v[10:11], s[14:15], v8, s25, v[2:3]
	v_mad_i32_i24 v11, v9, s25, v11
	v_lshl_add_u64 v[8:9], v[10:11], 0, s[8:9]
	v_lshl_add_u64 v[8:9], v[8:9], 0, v[6:7]
	v_lshl_add_u64 v[10:11], v[10:11], 0, s[6:7]
	v_lshl_add_u64 v[10:11], v[10:11], 0, v[0:1]
	global_load_dwordx4 v[40:43], v[8:9], off offset:1024
	global_load_dwordx2 v[90:91], v[10:11], off offset:512
	v_add_co_u32_e32 v8, vcc, s24, v8
	s_or_b32 s14, s10, 2
	s_nop 0
	v_addc_co_u32_e32 v9, vcc, 0, v9, vcc
	s_ashr_i32 s15, s14, 31
	s_or_b32 s18, s10, 5
	v_add_co_u32_e32 v10, vcc, s24, v10
	s_lshl_b64 s[14:15], s[14:15], 6
	s_ashr_i32 s19, s18, 31
	v_addc_co_u32_e32 v11, vcc, 0, v11, vcc
	global_load_dwordx4 v[44:47], v[8:9], off offset:2048
	global_load_dwordx2 v[92:93], v[10:11], off offset:1536
	v_lshl_add_u64 v[8:9], v[4:5], 0, s[14:15]
	s_lshl_b64 s[20:21], s[18:19], 6
	s_or_b32 s18, s10, 6
	v_mad_u64_u32 v[10:11], s[14:15], v8, s25, v[2:3]
	s_ashr_i32 s19, s18, 31
	s_or_b32 s14, s10, 3
	s_or_b32 s16, s10, 4
	s_lshl_b64 s[22:23], s[18:19], 6
	s_or_b32 s18, s10, 7
	s_add_i32 s10, s10, s78
	s_ashr_i32 s15, s14, 31
	s_ashr_i32 s17, s16, 31
	s_ashr_i32 s19, s18, 31
	s_ashr_i32 s11, s10, 31
	s_lshl_b64 s[14:15], s[14:15], 6
	s_lshl_b64 s[16:17], s[16:17], 6
	s_lshl_b64 s[18:19], s[18:19], 6
	s_lshl_b64 s[26:27], s[10:11], 6
	s_add_u32 s11, s26, s12
	s_addc_u32 s12, s27, s13
	v_or_b32_e32 v12, s11, v152
	v_mov_b32_e32 v13, s12
	v_lshlrev_b64 v[12:13], 5, v[12:13]
	v_lshl_add_u64 v[12:13], s[74:75], 0, v[12:13]
	v_lshl_add_u64 v[12:13], v[12:13], 0, s[4:5]
	s_mov_b64 s[4:5], 0x3000000
	v_lshl_add_u64 v[14:15], v[12:13], 0, s[4:5]
	s_mov_b32 s4, 0x3000000
	v_mad_i32_i24 v11, v9, s25, v11
	v_add_co_u32_e32 v12, vcc, s4, v12
	v_lshl_add_u64 v[8:9], v[10:11], 0, s[8:9]
	v_lshl_add_u64 v[10:11], v[10:11], 0, s[6:7]
	v_addc_co_u32_e32 v13, vcc, 0, v13, vcc
	v_lshl_add_u64 v[8:9], v[8:9], 0, v[6:7]
	v_lshl_add_u64 v[10:11], v[10:11], 0, v[0:1]
	global_load_dword v29, v[12:13], off
	s_nop 0
	global_load_dword v14, v[14:15], off offset:16
	s_nop 0
	global_load_dwordx4 v[64:67], v[8:9], off offset:1024
	global_load_dwordx2 v[102:103], v[10:11], off offset:512
	v_add_co_u32_e32 v8, vcc, s24, v8
	s_nop 1
	v_addc_co_u32_e32 v9, vcc, 0, v9, vcc
	v_add_co_u32_e32 v10, vcc, s24, v10
	s_nop 1
	v_addc_co_u32_e32 v11, vcc, 0, v11, vcc
	global_load_dwordx4 v[68:71], v[8:9], off offset:2048
	global_load_dwordx2 v[104:105], v[10:11], off offset:1536
	v_lshl_add_u64 v[8:9], v[4:5], 0, s[14:15]
; __device__ __forceinline__ float fast_tanh(float x) { return 1.f - 2.f * __builtin_amdgcn_rcpf(1.f + __expf(2.f * x)); }
; __device__ __forceinline__ void mlstm_state_group(const Args& a, LAS unsigned char* lds, int bh, int grp, int tid, int wave, int lane) {
;     ...
;     for (int ci = 0; ci < ML_GROUP; ++ci) { const size_t r0 = rowbase + (size_t)(c0 + ci) * 64;
; #pragma unroll
;         for (int i = 0; i < 2; ++i) { rv[ci][i] = *(const u32x4*)(P + (r0 + 2 * lp + i) * NIN + PC_VM + h * 128 + pcg * 8); rk2[ci][i] = *(const u32x2*)(P + (r0 + 2 * lp + i) * NIN + PC_KM + h * 64 + pcg * 4); } }
;     {
;         const size_t r = rowbase + (size_t)(c0 + wave) * 64 + lane;
;         const float gi = GT[r * 8 + h], gf = GT[r * 8 + 4 + h];
;         const float ipre = 15.f * fast_tanh((gi + b_i) * (1.f / 15.f)), fpre = 15.f * fast_tanh((gf + b_f) * (1.f / 15.f));
;         float bc = -__logf(1.f + __expf(-fpre));
; #pragma unroll
;         for (int o = 1; o < 64; o <<= 1) { const float t = __shfl_up(bc, o); if (lane >= o) bc += t; }
	v_mad_u64_u32 v[10:11], s[4:5], v8, s25, v[2:3]
	v_mad_i32_i24 v11, v9, s25, v11
	v_lshl_add_u64 v[8:9], v[10:11], 0, s[8:9]
	v_lshl_add_u64 v[8:9], v[8:9], 0, v[6:7]
	v_lshl_add_u64 v[10:11], v[10:11], 0, s[6:7]
	v_lshl_add_u64 v[10:11], v[10:11], 0, v[0:1]
	global_load_dwordx4 v[56:59], v[8:9], off offset:1024
	global_load_dwordx2 v[98:99], v[10:11], off offset:512
	v_add_co_u32_e32 v8, vcc, s24, v8
	s_nop 1
	v_addc_co_u32_e32 v9, vcc, 0, v9, vcc
	v_add_co_u32_e32 v10, vcc, s24, v10
	s_nop 1
	v_addc_co_u32_e32 v11, vcc, 0, v11, vcc
	global_load_dwordx4 v[60:63], v[8:9], off offset:2048
	global_load_dwordx2 v[100:101], v[10:11], off offset:1536
	v_lshl_add_u64 v[8:9], v[4:5], 0, s[16:17]
	v_mad_u64_u32 v[10:11], s[4:5], v8, s25, v[2:3]
	v_mad_i32_i24 v11, v9, s25, v11
	v_lshl_add_u64 v[8:9], v[10:11], 0, s[8:9]
	v_lshl_add_u64 v[8:9], v[8:9], 0, v[6:7]
	v_lshl_add_u64 v[10:11], v[10:11], 0, s[6:7]
	v_lshl_add_u64 v[10:11], v[10:11], 0, v[0:1]
	global_load_dwordx4 v[32:35], v[8:9], off offset:1024
	global_load_dwordx2 v[86:87], v[10:11], off offset:512
	v_add_co_u32_e32 v8, vcc, s24, v8
	s_nop 1
	v_addc_co_u32_e32 v9, vcc, 0, v9, vcc
	v_add_co_u32_e32 v10, vcc, s24, v10
	s_nop 1
	v_addc_co_u32_e32 v11, vcc, 0, v11, vcc
	global_load_dwordx4 v[36:39], v[8:9], off offset:2048
	global_load_dwordx2 v[88:89], v[10:11], off offset:1536
	v_lshl_add_u64 v[8:9], v[4:5], 0, s[20:21]
	v_mad_u64_u32 v[10:11], s[4:5], v8, s25, v[2:3]
	v_mad_i32_i24 v11, v9, s25, v11
	v_lshl_add_u64 v[8:9], v[10:11], 0, s[8:9]
	v_lshl_add_u64 v[8:9], v[8:9], 0, v[6:7]
	v_lshl_add_u64 v[10:11], v[10:11], 0, s[6:7]
	v_lshl_add_u64 v[10:11], v[10:11], 0, v[0:1]
	global_load_dwordx4 v[20:23], v[8:9], off offset:1024
	global_load_dwordx2 v[80:81], v[10:11], off offset:512
	v_add_co_u32_e32 v8, vcc, s24, v8
	s_nop 1
	v_addc_co_u32_e32 v9, vcc, 0, v9, vcc
	v_add_co_u32_e32 v10, vcc, s24, v10
	s_nop 1
	v_addc_co_u32_e32 v11, vcc, 0, v11, vcc
	global_load_dwordx4 v[24:27], v[8:9], off offset:2048
	global_load_dwordx2 v[82:83], v[10:11], off offset:1536
	v_lshl_add_u64 v[8:9], v[4:5], 0, s[22:23]
	v_mad_u64_u32 v[10:11], s[4:5], v8, s25, v[2:3]
	v_mad_i32_i24 v11, v9, s25, v11
	v_lshl_add_u64 v[8:9], v[10:11], 0, s[8:9]
	v_lshl_add_u64 v[12:13], v[8:9], 0, v[6:7]
	v_lshl_add_u64 v[8:9], v[10:11], 0, s[6:7]
	s_waitcnt vmcnt(16)
	v_add_f32_e32 v10, v16, v14
	v_mul_f32_e32 v10, 0x3d888889, v10
	v_add_f32_e32 v10, v10, v10
	v_mul_f32_e32 v10, 0x3fb8aa3b, v10
	v_exp_f32_e32 v16, v10
	v_lshl_add_u64 v[14:15], v[8:9], 0, v[0:1]
	global_load_dwordx4 v[8:11], v[12:13], off offset:1024
	global_load_dwordx2 v[74:75], v[14:15], off offset:512
	v_add_co_u32_e32 v12, vcc, s24, v12
	v_add_f32_e32 v16, 1.0, v16
	v_rcp_f32_e32 v16, v16
	v_addc_co_u32_e32 v13, vcc, 0, v13, vcc
	v_add_co_u32_e32 v14, vcc, s24, v14
	v_fma_f32 v16, v16, -2.0, 1.0
	v_mul_f32_e32 v16, 0xc1700000, v16
	v_mul_f32_e32 v16, 0x3fb8aa3b, v16
	v_exp_f32_e32 v16, v16
	v_addc_co_u32_e32 v15, vcc, 0, v15, vcc
	s_mov_b32 s4, 0x800000
	v_add_f32_e32 v16, 1.0, v16
	v_cmp_gt_f32_e32 vcc, s4, v16
	s_mov_b32 s4, 0x3f317217
	v_lshl_add_u64 v[4:5], v[4:5], 0, s[18:19]
	v_cndmask_b32_e64 v17, 0, 32, vcc
	v_ldexp_f32 v16, v16, v17
	v_log_f32_e32 v30, v16
	global_load_dwordx4 v[16:19], v[12:13], off offset:2048
	global_load_dwordx2 v[78:79], v[14:15], off offset:1536
	v_mbcnt_lo_u32_b32 v14, -1, 0
	v_mbcnt_hi_u32_b32 v72, -1, v14
	v_mul_f32_e32 v12, 0x3f317217, v30
	v_fma_f32 v12, v30, s4, -v12
	v_fmamk_f32 v12, v30, 0x3377d1cf, v12
	s_mov_b32 s4, 0x7f800000
	v_fmac_f32_e32 v12, 0x3f317217, v30
	v_cmp_lt_f32_e64 s[4:5], |v30|, s4
	v_mov_b32_e32 v13, 0x41b17218
	v_and_b32_e32 v73, 64, v72
	v_add_u32_e32 v14, -1, v72
	v_cndmask_b32_e64 v12, v30, v12, s[4:5]
	v_cndmask_b32_e32 v13, 0, v13, vcc
	v_cmp_lt_i32_e32 vcc, v14, v73
	v_sub_f32_e32 v12, v12, v13
	v_xor_b32_e32 v13, 0x80000000, v12
	v_cndmask_b32_e32 v14, v14, v72, vcc
	v_lshlrev_b32_e32 v14, 2, v14
	ds_bpermute_b32 v13, v14, v13
	v_mad_u64_u32 v[2:3], s[4:5], v4, s25, v[2:3]
	v_mad_i32_i24 v3, v5, s25, v3
	v_lshl_add_u64 v[4:5], v[2:3], 0, s[8:9]
	v_lshl_add_u64 v[4:5], v[4:5], 0, v[6:7]
	v_add_u32_e32 v7, -2, v72
	v_cmp_lt_i32_e64 s[4:5], v7, v73
	s_waitcnt lgkmcnt(0)
; __device__ __forceinline__ void mlstm_state_group(const Args& a, LAS unsigned char* lds, int bh, int grp, int tid, int wave, int lane) {
;     ...
;         for (int o = 1; o < 64; o <<= 1) { const float t = __shfl_up(bc, o); if (lane >= o) bc += t; }
;         const float bl = __shfl(bc, 63);
;         const float av = bl - bc + ipre;
;         float amax = av;
; #pragma unroll
;         for (int o = 1; o < 64; o <<= 1) amax = fmaxf(amax, __shfl_xor(amax, o));
;         T_av[wave * 64 + lane] = av;
;         if (lane == 0) { T_sc[wave] = bl; T_sc[8 + wave] = amax; CHS[(bh * 32 + c0 + wave) * 2] = bl; CHS[(bh * 32 + c0 + wave) * 2 + 1] = amax; }
	v_sub_f32_e32 v6, v13, v12
	v_cmp_eq_u32_e32 vcc, 0, v152
	v_cndmask_b32_e64 v7, v7, v72, s[4:5]
	v_lshlrev_b32_e32 v7, 2, v7
	v_cndmask_b32_e64 v6, v6, -v12, vcc
	ds_bpermute_b32 v7, v7, v6
	v_lshl_add_u64 v[2:3], v[2:3], 0, s[6:7]
	v_lshl_add_u64 v[0:1], v[2:3], 0, v[0:1]
	v_cmp_gt_u32_e64 s[4:5], 2, v152
	global_load_dwordx4 v[12:15], v[4:5], off offset:1024
	global_load_dwordx2 v[76:77], v[0:1], off offset:512
	s_waitcnt lgkmcnt(0)
	v_add_f32_e32 v2, v6, v7
	v_cndmask_b32_e64 v6, v2, v6, s[4:5]
	v_add_u32_e32 v2, -4, v72
	v_cmp_lt_i32_e64 s[4:5], v2, v73
	s_nop 1
	v_cndmask_b32_e64 v2, v2, v72, s[4:5]
	v_lshlrev_b32_e32 v2, 2, v2
	ds_bpermute_b32 v7, v2, v6
	v_add_co_u32_e64 v2, s[4:5], s24, v4
	s_waitcnt lgkmcnt(0)
	v_add_f32_e32 v4, v6, v7
	v_addc_co_u32_e64 v3, s[4:5], 0, v5, s[4:5]
	v_cmp_gt_u32_e64 s[4:5], 4, v152
	v_add_u32_e32 v5, -8, v72
	s_nop 0
	v_cndmask_b32_e64 v4, v4, v6, s[4:5]
	v_cmp_lt_i32_e64 s[4:5], v5, v73
	v_add_f32_e32 v6, v28, v29
	v_mul_f32_e32 v6, 0x3d888889, v6
	v_cndmask_b32_e64 v5, v5, v72, s[4:5]
	v_lshlrev_b32_e32 v5, 2, v5
	ds_bpermute_b32 v5, v5, v4
	v_add_co_u32_e64 v0, s[4:5], s24, v0
	v_add_f32_e32 v6, v6, v6
	s_nop 0
	v_addc_co_u32_e64 v1, s[4:5], 0, v1, s[4:5]
	s_waitcnt lgkmcnt(0)
	v_add_f32_e32 v5, v4, v5
	v_cmp_gt_u32_e64 s[4:5], 8, v152
	global_load_dwordx4 v[28:31], v[2:3], off offset:2048
	global_load_dwordx2 v[84:85], v[0:1], off offset:1536
	v_cndmask_b32_e64 v4, v5, v4, s[4:5]
	v_add_u32_e32 v5, -16, v72
	v_cmp_lt_i32_e64 s[4:5], v5, v73
	v_mul_f32_e32 v6, 0x3fb8aa3b, v6
	v_exp_f32_e32 v6, v6
	v_cndmask_b32_e64 v5, v5, v72, s[4:5]
	v_lshlrev_b32_e32 v5, 2, v5
	ds_bpermute_b32 v5, v5, v4
	v_cmp_gt_u32_e64 s[4:5], 16, v152
	v_add_f32_e32 v0, 1.0, v6
	v_rcp_f32_e32 v1, v0
	s_waitcnt lgkmcnt(0)
	v_add_f32_e32 v5, v4, v5
	v_cndmask_b32_e64 v4, v5, v4, s[4:5]
	v_subrev_u32_e32 v5, 32, v72
	v_cmp_lt_i32_e64 s[4:5], v5, v73
	v_fma_f32 v1, v1, -2.0, 1.0
	s_nop 0
	v_cndmask_b32_e64 v5, v5, v72, s[4:5]
	v_lshlrev_b32_e32 v5, 2, v5
	ds_bpermute_b32 v5, v5, v4
	v_cmp_gt_u32_e64 s[4:5], 32, v152
	s_waitcnt lgkmcnt(0)
	v_add_f32_e32 v0, v4, v5
	v_cndmask_b32_e64 v2, v0, v4, s[4:5]
	v_bfrev_b32_e32 v0, 0.5
	v_lshl_or_b32 v0, v72, 2, v0
	ds_bpermute_b32 v0, v0, v2
	v_xor_b32_e32 v4, 2, v72
	s_waitcnt lgkmcnt(0)
	v_sub_f32_e32 v2, v0, v2
	v_fmamk_f32 v3, v1, 0x41700000, v2
	v_add_u32_e32 v2, 64, v73
	v_xor_b32_e32 v1, 1, v72
	v_cmp_lt_i32_e64 s[4:5], v1, v2
	s_nop 1
	v_cndmask_b32_e64 v1, v72, v1, s[4:5]
	v_lshlrev_b32_e32 v107, 2, v1
	ds_bpermute_b32 v1, v107, v3
	v_cmp_lt_i32_e64 s[4:5], v4, v2
	s_waitcnt lgkmcnt(0)
	v_max_f32_e32 v1, v1, v1
	v_cndmask_b32_e64 v4, v72, v4, s[4:5]
	v_max_f32_e32 v1, v3, v1
	v_lshlrev_b32_e32 v106, 2, v4
	ds_bpermute_b32 v4, v106, v1
	s_waitcnt lgkmcnt(0)
	v_max_f32_e32 v4, v4, v4
	v_max_f32_e32 v1, v1, v4
	v_xor_b32_e32 v4, 4, v72
	v_cmp_lt_i32_e64 s[4:5], v4, v2
	s_nop 1
	v_cndmask_b32_e64 v4, v72, v4, s[4:5]
	v_lshlrev_b32_e32 v73, 2, v4
	ds_bpermute_b32 v4, v73, v1
	s_waitcnt lgkmcnt(0)
	v_max_f32_e32 v4, v4, v4
	v_max_f32_e32 v1, v1, v4
	v_xor_b32_e32 v4, 8, v72
	v_cmp_lt_i32_e64 s[4:5], v4, v2
	s_nop 1
	v_cndmask_b32_e64 v4, v72, v4, s[4:5]
	v_lshlrev_b32_e32 v4, 2, v4
	ds_bpermute_b32 v4, v4, v1
	s_waitcnt lgkmcnt(0)
	v_max_f32_e32 v4, v4, v4
	v_max_f32_e32 v1, v1, v4
	v_xor_b32_e32 v4, 16, v72
	v_cmp_lt_i32_e64 s[4:5], v4, v2
	s_nop 1
	v_cndmask_b32_e64 v4, v72, v4, s[4:5]
	v_lshlrev_b32_e32 v4, 2, v4
	ds_bpermute_b32 v4, v4, v1
	s_waitcnt lgkmcnt(0)
	v_max_f32_e32 v4, v4, v4
	v_max_f32_e32 v1, v1, v4
	v_xor_b32_e32 v4, 32, v72
	v_cmp_lt_i32_e64 s[4:5], v4, v2
	s_nop 1
	v_cndmask_b32_e64 v2, v72, v4, s[4:5]
	v_lshlrev_b32_e32 v2, 2, v2
	ds_bpermute_b32 v2, v2, v1
	s_lshl_b32 s4, s78, 8
	s_add_i32 s4, s4, 0
	v_lshl_add_u32 v4, v152, 2, s4
	v_add_u32_e32 v4, 0x1aa00, v4
	ds_write_b32 v4, v3
	s_and_saveexec_b64 s[4:5], vcc
	s_cbranch_execz .LBB0_1081
	s_lshl_b32 s6, s0, 6
	s_lshl_b32 s7, s10, 1
	s_add_i32 s6, s7, s6
	s_ashr_i32 s7, s6, 31
	s_lshl_b64 s[6:7], s[6:7], 2
	s_add_u32 s6, s74, s6
	s_addc_u32 s7, s75, s7
	s_lshl_b32 s8, s78, 2
	s_add_i32 s8, s8, 0
	s_waitcnt lgkmcnt(1)
	v_max_f32_e32 v2, v2, v2
	v_max_f32_e32 v1, v1, v1
	s_add_i32 s8, s8, 0x1ca00
	v_max_f32_e32 v1, v1, v2
	v_mov_b32_e32 v2, s8
	ds_write2_b32 v2, v0, v1 offset1:8
	v_mov_b32_e32 v2, 0x1e010000
	global_store_dwordx2 v2, v[0:1], s[6:7] offset:2048

; #define LAS __attribute__((address_space(3)))
; __device__ __forceinline__ unsigned cvt_pk_bf16(float lo, float hi) { unsigned r; asm volatile("v_cvt_pk_bf16_f32 %0, %1, %2" : "=v"(r) : "v"(lo), "v"(hi)); return r; }
; __device__ __forceinline__ void attn_item(const Args& a, LAS unsigned char* lds, int item, int tid, int wave, int lane) {
;     ...
;     for (int it = 0; it < 2; ++it) {
;         const int t = tid + 512 * it;
;         const int kc = (t >> 2) < 192 ? (t >> 2) : 191, kpos = q0 - 128 + kc, kposc = kpos < 0 ? 0 : kpos;
;         const bf16_t* kp = P + (rowbase + kposc) * NIN + PC_KA + kvh * 64 + grp * 16; kk[it][0] = *(const u32x4*)kp; kk[it][1] = *(const u32x4*)(kp + 8);
;         const bf16_t* vp = P + (rowbase + kposc) * NIN + PC_VA + kvh * 64 + grp * 16; vv[it][0] = *(const u32x4*)vp; vv[it][1] = *(const u32x4*)(vp + 8);
;         const float* tkp = rope + (rowbase + kposc) * 16;
; #pragma unroll
;         for (int q = 0; q < 4; ++q) tk[it][q] = *(const f32x4*)(tkp + 4 * q);
;         const int qi = (t >> 2) & 63, gq = t >> 8;
;         const size_t row = rowbase + q0 + qi;
;         const bf16_t* qp = P + row * NIN + PC_QA + (kvh * 4 + gq) * 64 + grp * 16; qq[it][0] = *(const u32x4*)qp; qq[it][1] = *(const u32x4*)(qp + 8);
;         const float* tqp = rope + row * 16;
;     ...
;             u32x4 o0, o1;
; #pragma unroll
;             for (int q = 0; q < 4; ++q) { o0[q] = cvt_pk_bf16(x[2 * q] * 0.125f, x[2 * q + 1] * 0.125f); o1[q] = cvt_pk_bf16(x[8 + 2 * q] * 0.125f, x[8 + 2 * q + 1] * 0.125f); }
;             *(LAS u32x4*)(QS + (gq * 64 + qi) * LP + grp * 16) = o0; *(LAS u32x4*)(QS + (gq * 64 + qi) * LP + grp * 16 + 8) = o1;
;         }
;     }
;     __syncthreads();
.LBB0_1100:
	s_or_b64 exec, exec, s[34:35]
	v_mul_f32_e32 v4, 0x3e000000, v37
	v_mul_f32_e32 v0, 0x3e000000, v0
	v_mul_f32_e32 v3, 0x3e000000, v36
	v_cvt_pk_bf16_f32 v4, v3, v4
	v_mul_f32_e32 v1, 0x3e000000, v1
	v_cvt_pk_bf16_f32 v8, v0, v1
	v_mul_f32_e32 v0, 0x3e000000, v34
	v_mul_f32_e32 v1, 0x3e000000, v35
	v_cvt_pk_bf16_f32 v5, v0, v1
	v_mul_f32_e32 v0, 0x3e000000, v24
	v_mul_f32_e32 v1, 0x3e000000, v25
	v_cvt_pk_bf16_f32 v9, v0, v1
	v_mul_f32_e32 v0, 0x3e000000, v32
	v_mul_f32_e32 v1, 0x3e000000, v33
	v_cvt_pk_bf16_f32 v6, v0, v1
	v_mul_f32_e32 v0, 0x3e000000, v28
	s_lshl_b32 s22, s44, 2
	v_mul_f32_e32 v1, 0x3e000000, v29
	v_cvt_pk_bf16_f32 v10, v0, v1
	v_mul_f32_e32 v0, 0x3e000000, v30
	s_add_i32 s22, s22, s33
	v_mul_f32_e32 v1, 0x3e000000, v31
	v_cvt_pk_bf16_f32 v7, v0, v1
	v_mul_f32_e32 v0, 0x3e000000, v20
	s_lshl_b32 s34, s22, 2
	v_mul_f32_e32 v1, 0x3e000000, v21
	v_cvt_pk_bf16_f32 v11, v0, v1
	v_mov_b32_e32 v0, s34
	ds_write_b128 v106, v[4:7] offset:53248
	ds_write_b128 v106, v[8:11] offset:53264
	s_waitcnt lgkmcnt(0)
	s_barrier
	v_mov_b32_e32 v40, v155
	v_and_b32_e32 v1, 64, v107
	v_xor_b32_e32 v0, 16, v107
	v_add_u32_e32 v1, 64, v1
	v_cmp_lt_i32_e32 vcc, v0, v1
	s_cmpk_lt_u32 s36, 0x80
	s_cselect_b64 s[34:35], -1, 0
	v_cndmask_b32_e32 v0, v107, v0, vcc
	v_lshlrev_b32_e32 v41, 2, v0
	v_xor_b32_e32 v0, 32, v107
	v_cmp_lt_i32_e32 vcc, v0, v1
	s_or_b32 s37, s37, 0xffffff80
	s_lshl_b32 s22, s22, 6
	v_cndmask_b32_e32 v0, v107, v0, vcc
	s_mov_b32 s45, 0
	v_lshlrev_b32_e32 v42, 2, v0
	s_sub_i32 s44, 0, s37
	v_or_b32_e32 v43, s36, v92
	s_mov_b64 s[36:37], -1
	s_lshl_b32 s22, s22, 1
	s_waitcnt vmcnt(0)
	s_cmp_eq_u32 s43, 3
	s_cbranch_scc1 .Lapf_skip
	s_add_i32 s32, s43, 1
	s_lshl_b32 s32, s32, 5
	s_add_i32 s32, s32, s81
	s_bfe_u32 s53, s32, 0x10005
	s_lshr_b32 s54, s32, 6
	s_lshl_b32 s55, s92, 1
	s_add_i32 s54, s54, s55
	s_lshl_b32 s54, s54, 11
	s_lshl_b32 s55, s81, 6
	s_add_i32 s70, s54, s55
	s_add_i32 s71, s55, 0xffffff80
	s_lshl_b32 s79, s53, 7
	s_add_i32 s79, s79, 0x1000
	s_lshl_b32 s80, s53, 9
	s_add_i32 s80, s80, 0xc00
	s_movk_i32 s82, 0x2400
	s_movk_i32 s83, 0xc0
	v_add_u32_e32 v148, s71, v153
	v_max_i32_e32 v148, 0, v148
	v_add_u32_e32 v148, s54, v148
	v_mul_lo_u32 v148, v148, s82
	v_add_u32_e32 v148, s79, v148
	v_subrev_u32_e32 v149, s83, v153
	v_min_u32_e32 v149, 0xff, v149
	v_lshrrev_b32_e32 v150, 2, v149
	v_and_b32_e32 v149, 3, v149
	v_add_u32_e32 v150, s70, v150
	v_mul_lo_u32 v150, v150, s82
	v_lshl_add_u32 v150, v149, 7, v150
	v_add_u32_e32 v150, s80, v150
	v_cmp_gt_u32_e64 s[66:67], s83, v153
	s_nop 1
	v_cndmask_b32_e64 v148, v150, v148, s[66:67]
	global_load_dword v151, v148, s[68:69]
	global_load_dword v151, v148, s[68:69] offset:256
	v_min_u32_e32 v244, 0xbf, v153
	v_add_u32_e32 v244, s71, v244
	v_max_i32_e32 v244, 0, v244
	v_add_lshl_u32 v244, s54, v244, 6
	global_load_dword v151, v244, s[20:21]
